# ffjob-kloop-eight-loads-in-flight
# speedup vs baseline: 1.0644x; 1.0007x over previous
.LBB0_486:
	v_lshl_add_u64 v[22:23], v[16:17], 0, s[0:1]
	v_lshl_add_u64 v[20:21], v[18:19], 0, s[0:1]
	v_add_co_u32_e32 v20, vcc, 0x2448000, v20
	s_add_u32 s0, s0, 0x400
	s_nop 0
	v_addc_co_u32_e32 v21, vcc, 0, v21, vcc
	s_addc_u32 s1, s1, 0
	s_cmpk_eq_i32 s0, 0x800
	global_load_dwordx4 v[42:45], v[22:23], off offset:-512
	global_load_dwordx4 v[46:49], v[20:21], off offset:0
	global_load_dwordx4 v[50:53], v[22:23], off offset:-448
	global_load_dwordx4 v[54:57], v[20:21], off offset:64
	global_load_dwordx4 v[58:61], v[22:23], off offset:-384
	global_load_dwordx4 v[62:65], v[20:21], off offset:128
	global_load_dwordx4 v[66:69], v[22:23], off offset:-320
	global_load_dwordx4 v[70:73], v[20:21], off offset:192
	global_load_dwordx4 v[74:77], v[22:23], off offset:-256
	global_load_dwordx4 v[78:81], v[20:21], off offset:256
	global_load_dwordx4 v[82:85], v[22:23], off offset:-192
	global_load_dwordx4 v[86:89], v[20:21], off offset:320
	global_load_dwordx4 v[90:93], v[22:23], off offset:-128
	global_load_dwordx4 v[94:97], v[20:21], off offset:384
	global_load_dwordx4 v[98:101], v[22:23], off offset:-64
	global_load_dwordx4 v[102:105], v[20:21], off offset:448
	s_waitcnt vmcnt(8)
	v_mfma_f32_16x16x32_bf16 v[2:5], v[42:45], v[46:49], v[2:5]
	v_mfma_f32_16x16x32_bf16 v[2:5], v[50:53], v[54:57], v[2:5]
	v_mfma_f32_16x16x32_bf16 v[2:5], v[58:61], v[62:65], v[2:5]
	v_mfma_f32_16x16x32_bf16 v[2:5], v[66:69], v[70:73], v[2:5]
	global_load_dwordx4 v[42:45], v[22:23], off offset:0
	global_load_dwordx4 v[46:49], v[20:21], off offset:512
	global_load_dwordx4 v[50:53], v[22:23], off offset:64
	global_load_dwordx4 v[54:57], v[20:21], off offset:576
	global_load_dwordx4 v[58:61], v[22:23], off offset:128
	global_load_dwordx4 v[62:65], v[20:21], off offset:640
	global_load_dwordx4 v[66:69], v[22:23], off offset:192
	global_load_dwordx4 v[70:73], v[20:21], off offset:704
	s_waitcnt vmcnt(8)
	v_mfma_f32_16x16x32_bf16 v[2:5], v[74:77], v[78:81], v[2:5]
	v_mfma_f32_16x16x32_bf16 v[2:5], v[82:85], v[86:89], v[2:5]
	v_mfma_f32_16x16x32_bf16 v[2:5], v[90:93], v[94:97], v[2:5]
	v_mfma_f32_16x16x32_bf16 v[2:5], v[98:101], v[102:105], v[2:5]
	global_load_dwordx4 v[74:77], v[22:23], off offset:256
	global_load_dwordx4 v[78:81], v[20:21], off offset:768
	global_load_dwordx4 v[82:85], v[22:23], off offset:320
	global_load_dwordx4 v[86:89], v[20:21], off offset:832
	global_load_dwordx4 v[90:93], v[22:23], off offset:384
	global_load_dwordx4 v[94:97], v[20:21], off offset:896
	global_load_dwordx4 v[98:101], v[22:23], off offset:448
	global_load_dwordx4 v[102:105], v[20:21], off offset:960
	s_waitcnt vmcnt(8)
	v_mfma_f32_16x16x32_bf16 v[2:5], v[42:45], v[46:49], v[2:5]
	v_mfma_f32_16x16x32_bf16 v[2:5], v[50:53], v[54:57], v[2:5]
	v_mfma_f32_16x16x32_bf16 v[2:5], v[58:61], v[62:65], v[2:5]
	v_mfma_f32_16x16x32_bf16 v[2:5], v[66:69], v[70:73], v[2:5]
	s_waitcnt vmcnt(0)
	v_mfma_f32_16x16x32_bf16 v[2:5], v[74:77], v[78:81], v[2:5]
	v_mfma_f32_16x16x32_bf16 v[2:5], v[82:85], v[86:89], v[2:5]
	v_mfma_f32_16x16x32_bf16 v[2:5], v[90:93], v[94:97], v[2:5]
	v_mfma_f32_16x16x32_bf16 v[2:5], v[98:101], v[102:105], v[2:5]
	s_cbranch_scc0 .LBB0_486
	s_and_saveexec_b64 s[0:1], s[36:37]
	s_cbranch_execz .LBB0_484
	v_lshl_add_u32 v0, s4, 7, v25
	v_or_b32_e32 v18, v0, v24
	v_ashrrev_i32_e32 v19, 31, v18
	v_lshlrev_b64 v[18:19], 6, v[18:19]
	v_lshl_add_u64 v[22:23], s[30:31], 0, v[18:19]
	global_load_dwordx4 v[18:21], v[22:23], off offset:48
	global_load_dwordx4 v[30:33], v[22:23], off offset:32
	global_load_dwordx4 v[34:37], v[22:23], off offset:16
	global_load_dwordx4 v[38:41], v[22:23], off
	s_movk_i32 s6, 0xfff
	s_mov_b32 s8, 0x42ce8ed0
	s_mov_b32 s9, 0xc2b17218
	s_mov_b32 s11, 0x3f2aaaab
	s_mov_b32 s12, 0x3f317218
	s_mov_b32 s10, 0x7f800000
	s_mov_b32 s13, 0x33800000
	s_waitcnt vmcnt(2)
	v_add_f32_e32 v30, v30, v31
	v_add_f32_e32 v32, v32, v33
	s_waitcnt vmcnt(0)
	v_mov_b32_e32 v22, v39
	v_mov_b32_e32 v23, v40
	v_mov_b32_e32 v39, v41
	v_pk_add_f32 v[22:23], v[22:23], v[38:39]
	v_mov_b32_e32 v38, v35
	v_mov_b32_e32 v39, v36
	v_mov_b32_e32 v35, v37
	v_pk_add_f32 v[34:35], v[38:39], v[34:35]
	v_pk_add_f32 v[22:23], v[22:23], v[22:23] op_sel:[0,1] op_sel_hi:[1,0]
	v_pk_add_f32 v[34:35], v[34:35], v[34:35] op_sel:[0,1] op_sel_hi:[1,0]
	v_mov_b32_e32 v23, v18
	v_mov_b32_e32 v35, v19
	v_mov_b32_e32 v31, v20
	v_mov_b32_e32 v33, v21
	v_pk_add_f32 v[18:19], v[22:23], v[34:35]
	v_pk_add_f32 v[20:21], v[30:31], v[32:33]
	s_nop 0
	v_pk_add_f32 v[18:19], v[18:19], v[20:21]
	s_nop 0
	v_add_f32_e32 v7, v18, v19
	v_fmamk_f32 v7, v7, 0x3a800000, v214
	v_bitop3_b32 v18, v0, s6, v24 bitop3:0xc8
	v_ashrrev_i32_e32 v0, 9, v0
	v_readlane_b32 s6, v252, 20
	v_rsq_f32_e32 v15, v7
	v_and_b32_e32 v7, -8, v0
	v_lshlrev_b32_e32 v0, 2, v18
	v_readlane_b32 s7, v252, 21
	s_nop 1
	v_lshl_add_u64 v[18:19], s[6:7], 0, v[0:1]
	global_load_dword v0, v[8:9], off
	s_mov_b32 s6, 0xbfb8aa3b
	s_mov_b32 s7, 0xb2a5705f
	s_waitcnt vmcnt(0)
	v_fmac_f32_e32 v0, v2, v15
	v_mul_f32_e64 v20, |v0|, s6
	v_fma_f32 v21, |v0|, s6, -v20
	v_rndne_f32_e32 v22, v20
	v_fma_f32 v21, |v0|, s7, v21
	v_sub_f32_e32 v20, v20, v22
	v_add_f32_e32 v20, v20, v21
	v_exp_f32_e32 v20, v20
	v_cvt_i32_f32_e32 v21, v22
	v_cmp_ngt_f32_e64 vcc, |v0|, s8
	v_min_f32_e32 v2, 0, v0
	v_ldexp_f32 v20, v20, v21
	v_cndmask_b32_e32 v20, 0, v20, vcc
	v_cmp_nlt_f32_e64 vcc, |v0|, s9
	s_nop 1
	v_cndmask_b32_e32 v0, v223, v20, vcc
	v_add_f32_e32 v22, 1.0, v0
	v_add_f32_e32 v20, -1.0, v22
	v_sub_f32_e32 v21, v20, v22
	v_add_f32_e32 v21, 1.0, v21
	v_sub_f32_e32 v20, v0, v20
	v_add_f32_e32 v23, v20, v21
	v_frexp_mant_f32_e32 v20, v22
	v_cmp_gt_f32_e32 vcc, s11, v20
	v_cvt_f64_f32_e32 v[20:21], v22
	v_frexp_exp_i32_f64_e32 v20, v[20:21]
	v_subbrev_co_u32_e32 v20, vcc, 0, v20, vcc
	v_sub_u32_e32 v21, 0, v20
	v_ldexp_f32 v22, v22, v21
	v_ldexp_f32 v21, v23, v21
	v_add_f32_e32 v23, -1.0, v22
	v_add_f32_e32 v29, 1.0, v23
	v_sub_f32_e32 v29, v22, v29
	v_add_f32_e32 v29, v21, v29
	v_add_f32_e32 v30, v23, v29
	v_sub_f32_e32 v23, v23, v30
	v_add_f32_e32 v23, v29, v23
	v_add_f32_e32 v29, 1.0, v22
	v_add_f32_e32 v31, -1.0, v29
	v_sub_f32_e32 v22, v22, v31
	v_add_f32_e32 v21, v21, v22
	v_add_f32_e32 v22, v29, v21
	v_sub_f32_e32 v29, v29, v22
	v_add_f32_e32 v21, v21, v29
	v_rcp_f32_e32 v29, v22
	v_cvt_f32_i32_e32 v20, v20
	v_cmp_neq_f32_e32 vcc, s10, v0
	v_mul_f32_e32 v31, v30, v29
	v_mul_f32_e32 v32, v22, v31
	v_fma_f32 v33, v31, v22, -v32
	v_fmac_f32_e32 v33, v31, v21
	v_add_f32_e32 v34, v32, v33
	v_sub_f32_e32 v35, v30, v34
	v_sub_f32_e32 v30, v30, v35
	v_sub_f32_e32 v32, v34, v32
	v_sub_f32_e32 v30, v30, v34
	v_add_f32_e32 v23, v23, v30
	v_sub_f32_e32 v30, v32, v33
	v_add_f32_e32 v23, v30, v23
	v_add_f32_e32 v30, v35, v23
	v_mul_f32_e32 v32, v29, v30
	v_mul_f32_e32 v33, v22, v32
	v_fma_f32 v22, v32, v22, -v33
	v_fmac_f32_e32 v22, v32, v21
	v_sub_f32_e32 v21, v35, v30
	v_add_f32_e32 v21, v23, v21
	v_add_f32_e32 v23, v33, v22
	v_sub_f32_e32 v34, v30, v23
	v_sub_f32_e32 v30, v30, v34
	v_sub_f32_e32 v33, v23, v33
	v_sub_f32_e32 v23, v30, v23
	v_add_f32_e32 v21, v21, v23
	v_sub_f32_e32 v22, v33, v22
	v_add_f32_e32 v21, v22, v21
	v_add_f32_e32 v22, v31, v32
	v_add_f32_e32 v21, v34, v21
	v_sub_f32_e32 v23, v22, v31
	v_mul_f32_e32 v21, v29, v21
	v_sub_f32_e32 v23, v32, v23
	v_add_f32_e32 v21, v23, v21
	v_mul_f32_e32 v31, 0x3f317218, v20
	v_add_f32_e32 v23, v22, v21
	v_fma_f32 v32, v20, s12, -v31
	v_mul_f32_e32 v29, v23, v23
	v_fmac_f32_e32 v32, 0xb102e308, v20
	v_sub_f32_e32 v20, v23, v22
	v_fmamk_f32 v30, v29, 0x3e9b6dac, v215
	v_sub_f32_e32 v20, v21, v20
	v_add_f32_e32 v21, v31, v32
	v_fmaak_f32 v30, v29, v30, 0x3f2aaada
	v_sub_f32_e32 v22, v21, v31
	v_ldexp_f32 v31, v23, 1
	v_mul_f32_e32 v23, v23, v29
	v_mul_f32_e32 v23, v23, v30
	v_add_f32_e32 v29, v31, v23
	v_sub_f32_e32 v30, v29, v31
	v_ldexp_f32 v20, v20, 1
	v_sub_f32_e32 v23, v23, v30
	v_add_f32_e32 v20, v20, v23
	v_add_f32_e32 v23, v29, v20
	v_sub_f32_e32 v29, v23, v29
	v_sub_f32_e32 v20, v20, v29
	v_add_f32_e32 v29, v21, v23
	v_sub_f32_e32 v30, v29, v21
	v_sub_f32_e32 v31, v29, v30
	v_sub_f32_e32 v22, v32, v22
	v_sub_f32_e32 v21, v21, v31
	v_sub_f32_e32 v23, v23, v30
	v_add_f32_e32 v21, v23, v21
	v_add_f32_e32 v23, v22, v20
	v_sub_f32_e32 v30, v23, v22
	v_sub_f32_e32 v31, v23, v30
	v_sub_f32_e32 v22, v22, v31
	v_sub_f32_e32 v20, v20, v30
	v_add_f32_e32 v21, v23, v21
	v_add_f32_e32 v20, v20, v22
	v_add_f32_e32 v22, v29, v21
	v_sub_f32_e32 v23, v22, v29
	v_sub_f32_e32 v21, v21, v23
	v_add_f32_e32 v20, v20, v21
	v_add_f32_e32 v20, v22, v20
	v_cndmask_b32_e32 v20, v223, v20, vcc
	v_cmp_lt_f32_e64 vcc, |v0|, s13
	s_nop 1
	v_cndmask_b32_e32 v0, v20, v0, vcc
	v_or_b32_e32 v20, v7, v6
	v_ashrrev_i32_e32 v21, 31, v20
	v_lshlrev_b64 v[20:21], 14, v[20:21]
	v_sub_f32_e32 v0, v2, v0
	v_lshl_add_u64 v[20:21], v[18:19], 0, v[20:21]
	global_store_dword v[20:21], v0, off
	global_load_dword v0, v[10:11], off offset:4
	s_waitcnt vmcnt(0)
	v_fmac_f32_e32 v0, v3, v15
	v_mul_f32_e64 v2, |v0|, s6
	v_fma_f32 v3, |v0|, s6, -v2
	v_rndne_f32_e32 v21, v2
	v_fma_f32 v3, |v0|, s7, v3
	v_sub_f32_e32 v2, v2, v21
	v_add_f32_e32 v2, v2, v3
	v_exp_f32_e32 v2, v2
	v_cvt_i32_f32_e32 v3, v21
	v_cmp_ngt_f32_e64 vcc, |v0|, s8
	v_min_f32_e32 v20, 0, v0
	v_ldexp_f32 v2, v2, v3
	v_cndmask_b32_e32 v2, 0, v2, vcc
	v_cmp_nlt_f32_e64 vcc, |v0|, s9
	s_nop 1
	v_cndmask_b32_e32 v0, v223, v2, vcc
	v_add_f32_e32 v21, 1.0, v0
	v_add_f32_e32 v2, -1.0, v21
	v_sub_f32_e32 v3, v2, v21
	v_add_f32_e32 v3, 1.0, v3
	v_sub_f32_e32 v2, v0, v2
	v_add_f32_e32 v22, v2, v3
	v_frexp_mant_f32_e32 v2, v21
	v_cmp_gt_f32_e32 vcc, s11, v2
	v_cvt_f64_f32_e32 v[2:3], v21
	v_frexp_exp_i32_f64_e32 v2, v[2:3]
	v_subbrev_co_u32_e32 v2, vcc, 0, v2, vcc
	v_sub_u32_e32 v3, 0, v2
	v_ldexp_f32 v21, v21, v3
	v_ldexp_f32 v3, v22, v3
	v_add_f32_e32 v22, -1.0, v21
	v_add_f32_e32 v23, 1.0, v22
	v_sub_f32_e32 v23, v21, v23
	v_add_f32_e32 v23, v3, v23
	v_add_f32_e32 v29, v22, v23
	v_sub_f32_e32 v22, v22, v29
	v_add_f32_e32 v22, v23, v22
	v_add_f32_e32 v23, 1.0, v21
	v_add_f32_e32 v30, -1.0, v23
	v_sub_f32_e32 v21, v21, v30
	v_add_f32_e32 v3, v3, v21
	v_add_f32_e32 v21, v23, v3
	v_sub_f32_e32 v23, v23, v21
	v_add_f32_e32 v3, v3, v23
	v_rcp_f32_e32 v23, v21
	v_cvt_f32_i32_e32 v2, v2
	v_cmp_neq_f32_e32 vcc, s10, v0
	v_mul_f32_e32 v30, v29, v23
	v_mul_f32_e32 v31, v21, v30
	v_fma_f32 v32, v30, v21, -v31
	v_fmac_f32_e32 v32, v30, v3
	v_add_f32_e32 v33, v31, v32
	v_sub_f32_e32 v34, v29, v33
	v_sub_f32_e32 v29, v29, v34
	v_sub_f32_e32 v31, v33, v31
	v_sub_f32_e32 v29, v29, v33
	v_add_f32_e32 v22, v22, v29
	v_sub_f32_e32 v29, v31, v32
	v_add_f32_e32 v22, v29, v22
	v_add_f32_e32 v29, v34, v22
	v_mul_f32_e32 v31, v23, v29
	v_mul_f32_e32 v32, v21, v31
	v_fma_f32 v21, v31, v21, -v32
	v_fmac_f32_e32 v21, v31, v3
	v_sub_f32_e32 v3, v34, v29
	v_add_f32_e32 v3, v22, v3
	v_add_f32_e32 v22, v32, v21
	v_sub_f32_e32 v33, v29, v22
	v_sub_f32_e32 v29, v29, v33
	v_sub_f32_e32 v32, v22, v32
	v_sub_f32_e32 v22, v29, v22
	v_add_f32_e32 v3, v3, v22
	v_sub_f32_e32 v21, v32, v21
	v_add_f32_e32 v3, v21, v3
	v_add_f32_e32 v21, v30, v31
	v_add_f32_e32 v3, v33, v3
	v_sub_f32_e32 v22, v21, v30
	v_mul_f32_e32 v3, v23, v3
	v_sub_f32_e32 v22, v31, v22
	v_add_f32_e32 v3, v22, v3
	v_mul_f32_e32 v30, 0x3f317218, v2
	v_add_f32_e32 v22, v21, v3
	v_fma_f32 v31, v2, s12, -v30
	v_mul_f32_e32 v23, v22, v22
	v_fmac_f32_e32 v31, 0xb102e308, v2
	v_sub_f32_e32 v2, v22, v21
	v_fmamk_f32 v29, v23, 0x3e9b6dac, v215
	v_sub_f32_e32 v2, v3, v2
	v_add_f32_e32 v3, v30, v31
	v_fmaak_f32 v29, v23, v29, 0x3f2aaada
	v_sub_f32_e32 v21, v3, v30
	v_ldexp_f32 v30, v22, 1
	v_mul_f32_e32 v22, v22, v23
	v_mul_f32_e32 v22, v22, v29
	v_add_f32_e32 v23, v30, v22
	v_sub_f32_e32 v29, v23, v30
	v_ldexp_f32 v2, v2, 1
	v_sub_f32_e32 v22, v22, v29
	v_add_f32_e32 v2, v2, v22
	v_add_f32_e32 v22, v23, v2
	v_sub_f32_e32 v23, v22, v23
	v_sub_f32_e32 v2, v2, v23
	v_add_f32_e32 v23, v3, v22
	v_sub_f32_e32 v29, v23, v3
	v_sub_f32_e32 v30, v23, v29
	v_sub_f32_e32 v21, v31, v21
	v_sub_f32_e32 v3, v3, v30
	v_sub_f32_e32 v22, v22, v29
	v_add_f32_e32 v3, v22, v3
	v_add_f32_e32 v22, v21, v2
	v_sub_f32_e32 v29, v22, v21
	v_sub_f32_e32 v30, v22, v29
	v_sub_f32_e32 v21, v21, v30
	v_sub_f32_e32 v2, v2, v29
	v_add_f32_e32 v3, v22, v3
	v_add_f32_e32 v2, v2, v21
	v_add_f32_e32 v21, v23, v3
	v_sub_f32_e32 v22, v21, v23
	v_sub_f32_e32 v3, v3, v22
	v_add_f32_e32 v2, v2, v3
	v_add_f32_e32 v2, v21, v2
	v_cndmask_b32_e32 v2, v223, v2, vcc
	v_cmp_lt_f32_e64 vcc, |v0|, s13
	s_nop 1
	v_cndmask_b32_e32 v0, v2, v0, vcc
	v_or_b32_e32 v2, v7, v26
	v_ashrrev_i32_e32 v3, 31, v2
	v_lshlrev_b64 v[2:3], 14, v[2:3]
	v_sub_f32_e32 v0, v20, v0
	v_lshl_add_u64 v[2:3], v[18:19], 0, v[2:3]
	global_store_dword v[2:3], v0, off
	global_load_dword v0, v[10:11], off offset:8
	s_waitcnt vmcnt(0)
	v_fmac_f32_e32 v0, v4, v15
	v_mul_f32_e64 v2, |v0|, s6
	v_fma_f32 v3, |v0|, s6, -v2
	v_rndne_f32_e32 v20, v2
	v_fma_f32 v3, |v0|, s7, v3
	v_sub_f32_e32 v2, v2, v20
	v_add_f32_e32 v2, v2, v3
	v_exp_f32_e32 v2, v2
	v_cvt_i32_f32_e32 v3, v20
	v_cmp_ngt_f32_e64 vcc, |v0|, s8
	v_min_f32_e32 v4, 0, v0
	v_ldexp_f32 v2, v2, v3
	v_cndmask_b32_e32 v2, 0, v2, vcc
	v_cmp_nlt_f32_e64 vcc, |v0|, s9
	s_nop 1
	v_cndmask_b32_e32 v0, v223, v2, vcc
	v_add_f32_e32 v20, 1.0, v0
	v_add_f32_e32 v2, -1.0, v20
	v_sub_f32_e32 v3, v2, v20
	v_add_f32_e32 v3, 1.0, v3
	v_sub_f32_e32 v2, v0, v2
	v_add_f32_e32 v21, v2, v3
	v_frexp_mant_f32_e32 v2, v20
	v_cmp_gt_f32_e32 vcc, s11, v2
	v_cvt_f64_f32_e32 v[2:3], v20
	v_frexp_exp_i32_f64_e32 v2, v[2:3]
	v_subbrev_co_u32_e32 v2, vcc, 0, v2, vcc
	v_sub_u32_e32 v3, 0, v2
	v_ldexp_f32 v20, v20, v3
	v_ldexp_f32 v3, v21, v3
	v_add_f32_e32 v21, -1.0, v20
	v_add_f32_e32 v22, 1.0, v21
	v_sub_f32_e32 v22, v20, v22
	v_add_f32_e32 v22, v3, v22
	v_add_f32_e32 v23, v21, v22
	v_sub_f32_e32 v21, v21, v23
	v_add_f32_e32 v21, v22, v21
	v_add_f32_e32 v22, 1.0, v20
	v_add_f32_e32 v29, -1.0, v22
	v_sub_f32_e32 v20, v20, v29
	v_add_f32_e32 v3, v3, v20
	v_add_f32_e32 v20, v22, v3
	v_sub_f32_e32 v22, v22, v20
	v_add_f32_e32 v3, v3, v22
	v_rcp_f32_e32 v22, v20
	v_cvt_f32_i32_e32 v2, v2
	v_cmp_neq_f32_e32 vcc, s10, v0
	v_mul_f32_e32 v29, v23, v22
	v_mul_f32_e32 v30, v20, v29
	v_fma_f32 v31, v29, v20, -v30
	v_fmac_f32_e32 v31, v29, v3
	v_add_f32_e32 v32, v30, v31
	v_sub_f32_e32 v33, v23, v32
	v_sub_f32_e32 v23, v23, v33
	v_sub_f32_e32 v30, v32, v30
	v_sub_f32_e32 v23, v23, v32
	v_add_f32_e32 v21, v21, v23
	v_sub_f32_e32 v23, v30, v31
	v_add_f32_e32 v21, v23, v21
	v_add_f32_e32 v23, v33, v21
	v_mul_f32_e32 v30, v22, v23
	v_mul_f32_e32 v31, v20, v30
	v_fma_f32 v20, v30, v20, -v31
	v_fmac_f32_e32 v20, v30, v3
	v_sub_f32_e32 v3, v33, v23
	v_add_f32_e32 v3, v21, v3
	v_add_f32_e32 v21, v31, v20
	v_sub_f32_e32 v32, v23, v21
	v_sub_f32_e32 v23, v23, v32
	v_sub_f32_e32 v31, v21, v31
	v_sub_f32_e32 v21, v23, v21
	v_add_f32_e32 v3, v3, v21
	v_sub_f32_e32 v20, v31, v20
	v_add_f32_e32 v3, v20, v3
	v_add_f32_e32 v20, v29, v30
	v_add_f32_e32 v3, v32, v3
	v_sub_f32_e32 v21, v20, v29
	v_mul_f32_e32 v3, v22, v3
	v_sub_f32_e32 v21, v30, v21
	v_add_f32_e32 v3, v21, v3
	v_mul_f32_e32 v29, 0x3f317218, v2
	v_add_f32_e32 v21, v20, v3
	v_fma_f32 v30, v2, s12, -v29
	v_mul_f32_e32 v22, v21, v21
	v_fmac_f32_e32 v30, 0xb102e308, v2
	v_sub_f32_e32 v2, v21, v20
	v_fmamk_f32 v23, v22, 0x3e9b6dac, v215
	v_sub_f32_e32 v2, v3, v2
	v_add_f32_e32 v3, v29, v30
	v_fmaak_f32 v23, v22, v23, 0x3f2aaada
	v_sub_f32_e32 v20, v3, v29
	v_ldexp_f32 v29, v21, 1
	v_mul_f32_e32 v21, v21, v22
	v_mul_f32_e32 v21, v21, v23
	v_add_f32_e32 v22, v29, v21
	v_sub_f32_e32 v23, v22, v29
	v_ldexp_f32 v2, v2, 1
	v_sub_f32_e32 v21, v21, v23
	v_add_f32_e32 v2, v2, v21
	v_add_f32_e32 v21, v22, v2
	v_sub_f32_e32 v22, v21, v22
	v_sub_f32_e32 v2, v2, v22
	v_add_f32_e32 v22, v3, v21
	v_sub_f32_e32 v23, v22, v3
	v_sub_f32_e32 v29, v22, v23
	v_sub_f32_e32 v20, v30, v20
	v_sub_f32_e32 v3, v3, v29
	v_sub_f32_e32 v21, v21, v23
	v_add_f32_e32 v3, v21, v3
	v_add_f32_e32 v21, v20, v2
	v_sub_f32_e32 v23, v21, v20
	v_sub_f32_e32 v29, v21, v23
	v_sub_f32_e32 v20, v20, v29
	v_sub_f32_e32 v2, v2, v23
	v_add_f32_e32 v3, v21, v3
	v_add_f32_e32 v2, v2, v20
	v_add_f32_e32 v20, v22, v3
	v_sub_f32_e32 v21, v20, v22
	v_sub_f32_e32 v3, v3, v21
	v_add_f32_e32 v2, v2, v3
	v_add_f32_e32 v2, v20, v2
	v_cndmask_b32_e32 v2, v223, v2, vcc
	v_cmp_lt_f32_e64 vcc, |v0|, s13
	s_nop 1
	v_cndmask_b32_e32 v0, v2, v0, vcc
	v_or_b32_e32 v2, v7, v27
	v_ashrrev_i32_e32 v3, 31, v2
	v_lshlrev_b64 v[2:3], 14, v[2:3]
	v_sub_f32_e32 v0, v4, v0
	v_lshl_add_u64 v[2:3], v[18:19], 0, v[2:3]
	global_store_dword v[2:3], v0, off
	global_load_dword v0, v[10:11], off offset:12
	s_waitcnt vmcnt(0)
	v_fmac_f32_e32 v0, v5, v15
	v_mul_f32_e64 v2, |v0|, s6
	v_fma_f32 v3, |v0|, s6, -v2
	v_rndne_f32_e32 v5, v2
	v_fma_f32 v3, |v0|, s7, v3
	v_sub_f32_e32 v2, v2, v5
	v_add_f32_e32 v2, v2, v3
	v_exp_f32_e32 v2, v2
	v_cvt_i32_f32_e32 v3, v5
	v_cmp_ngt_f32_e64 vcc, |v0|, s8
	v_min_f32_e32 v4, 0, v0
	v_ldexp_f32 v2, v2, v3
	v_cndmask_b32_e32 v2, 0, v2, vcc
	v_cmp_nlt_f32_e64 vcc, |v0|, s9
	s_nop 1
	v_cndmask_b32_e32 v0, v223, v2, vcc
	v_add_f32_e32 v5, 1.0, v0
	v_add_f32_e32 v2, -1.0, v5
	v_sub_f32_e32 v3, v2, v5
	v_add_f32_e32 v3, 1.0, v3
	v_sub_f32_e32 v2, v0, v2
	v_add_f32_e32 v15, v2, v3
	v_frexp_mant_f32_e32 v2, v5
	v_cmp_gt_f32_e32 vcc, s11, v2
	v_cvt_f64_f32_e32 v[2:3], v5
	v_frexp_exp_i32_f64_e32 v2, v[2:3]
	v_subbrev_co_u32_e32 v2, vcc, 0, v2, vcc
	v_sub_u32_e32 v3, 0, v2
	v_ldexp_f32 v5, v5, v3
	v_ldexp_f32 v3, v15, v3
	v_add_f32_e32 v15, -1.0, v5
	v_add_f32_e32 v20, 1.0, v15
	v_sub_f32_e32 v20, v5, v20
	v_add_f32_e32 v20, v3, v20
	v_add_f32_e32 v21, v15, v20
	v_sub_f32_e32 v15, v15, v21
	v_add_f32_e32 v15, v20, v15
	v_add_f32_e32 v20, 1.0, v5
	v_add_f32_e32 v22, -1.0, v20
	v_sub_f32_e32 v5, v5, v22
	v_add_f32_e32 v3, v3, v5
	v_add_f32_e32 v5, v20, v3
	v_sub_f32_e32 v20, v20, v5
	v_add_f32_e32 v3, v3, v20
	v_rcp_f32_e32 v20, v5
	v_cvt_f32_i32_e32 v2, v2
	v_cmp_neq_f32_e32 vcc, s10, v0
	v_mul_f32_e32 v22, v21, v20
	v_mul_f32_e32 v23, v5, v22
	v_fma_f32 v29, v22, v5, -v23
	v_fmac_f32_e32 v29, v22, v3
	v_add_f32_e32 v30, v23, v29
	v_sub_f32_e32 v31, v21, v30
	v_sub_f32_e32 v21, v21, v31
	v_sub_f32_e32 v23, v30, v23
	v_sub_f32_e32 v21, v21, v30
	v_add_f32_e32 v15, v15, v21
	v_sub_f32_e32 v21, v23, v29
	v_add_f32_e32 v15, v21, v15
	v_add_f32_e32 v21, v31, v15
	v_mul_f32_e32 v23, v20, v21
	v_mul_f32_e32 v29, v5, v23
	v_fma_f32 v5, v23, v5, -v29
	v_fmac_f32_e32 v5, v23, v3
	v_sub_f32_e32 v3, v31, v21
	v_add_f32_e32 v3, v15, v3
	v_add_f32_e32 v15, v29, v5
	v_sub_f32_e32 v30, v21, v15
	v_sub_f32_e32 v21, v21, v30
	v_sub_f32_e32 v29, v15, v29
	v_sub_f32_e32 v15, v21, v15
	v_add_f32_e32 v3, v3, v15
	v_sub_f32_e32 v5, v29, v5
	v_add_f32_e32 v3, v5, v3
	v_add_f32_e32 v5, v22, v23
	v_add_f32_e32 v3, v30, v3
	v_sub_f32_e32 v15, v5, v22
	v_mul_f32_e32 v3, v20, v3
	v_sub_f32_e32 v15, v23, v15
	v_add_f32_e32 v3, v15, v3
	v_mul_f32_e32 v22, 0x3f317218, v2
	v_add_f32_e32 v15, v5, v3
	v_fma_f32 v23, v2, s12, -v22
	v_mul_f32_e32 v20, v15, v15
	v_fmac_f32_e32 v23, 0xb102e308, v2
	v_sub_f32_e32 v2, v15, v5
	v_fmamk_f32 v21, v20, 0x3e9b6dac, v215
	v_sub_f32_e32 v2, v3, v2
	v_add_f32_e32 v3, v22, v23
	v_fmaak_f32 v21, v20, v21, 0x3f2aaada
	v_sub_f32_e32 v5, v3, v22
	v_ldexp_f32 v22, v15, 1
	v_mul_f32_e32 v15, v15, v20
	v_mul_f32_e32 v15, v15, v21
	v_add_f32_e32 v20, v22, v15
	v_sub_f32_e32 v21, v20, v22
	v_ldexp_f32 v2, v2, 1
	v_sub_f32_e32 v15, v15, v21
	v_add_f32_e32 v2, v2, v15
	v_add_f32_e32 v15, v20, v2
	v_sub_f32_e32 v20, v15, v20
	v_sub_f32_e32 v2, v2, v20
	v_add_f32_e32 v20, v3, v15
	v_sub_f32_e32 v21, v20, v3
	v_sub_f32_e32 v22, v20, v21
	v_sub_f32_e32 v5, v23, v5
	v_sub_f32_e32 v3, v3, v22
	v_sub_f32_e32 v15, v15, v21
	v_add_f32_e32 v3, v15, v3
	v_add_f32_e32 v15, v5, v2
	v_sub_f32_e32 v21, v15, v5
	v_sub_f32_e32 v22, v15, v21
	v_sub_f32_e32 v5, v5, v22
	v_sub_f32_e32 v2, v2, v21
	v_add_f32_e32 v3, v15, v3
	v_add_f32_e32 v2, v2, v5
	v_add_f32_e32 v5, v20, v3
	v_sub_f32_e32 v15, v5, v20
	v_sub_f32_e32 v3, v3, v15
	v_add_f32_e32 v2, v2, v3
	v_add_f32_e32 v2, v5, v2
	v_cndmask_b32_e32 v2, v223, v2, vcc
	v_cmp_lt_f32_e64 vcc, |v0|, s13
	s_nop 1
	v_cndmask_b32_e32 v0, v2, v0, vcc
	v_or_b32_e32 v2, v7, v28
	v_ashrrev_i32_e32 v3, 31, v2
	v_lshlrev_b64 v[2:3], 14, v[2:3]
	v_sub_f32_e32 v0, v4, v0
	v_lshl_add_u64 v[2:3], v[18:19], 0, v[2:3]
	global_store_dword v[2:3], v0, off
	s_branch .LBB0_484
